# long-conv MFMA groups: resident-A MFMAs first, new A fragment read gets two more MFMA slots
# speedup vs baseline: 1.0012x; 1.0012x over previous
; #define MFMA(a, b, c) __builtin_amdgcn_mfma_f32_32x32x16_bf16((a), (b), (c), 0, 0, 0)
; __device__ __forceinline__ void toeplitz_item(const Params& p, int layer, int half, int c, bf16* sm, int dry, unsigned* done_ctr) {
;     ...
;     for (int Dl = 0; Dl < 4; ++Dl) {
;       const int D = D0 + Dl;
;       bool actv[2];
;       int bblk[2];
; #pragma unroll
;       for (int ni = 0; ni < 2; ++ni) {
;         const int nlo = 32 * wn + 64 * ni;
;         actv[ni] = half ? true : !((nlo + 31 - D < 0) || (nlo - D >= 128));
;         const int n = nlo + r;
;         const int src = n - D;
;         const bool valid = half ? ((unsigned)((n & 15) - D) < 16u) : ((unsigned)src < 128u);
;         bblk[ni] = valid ? src : 128;
;       }
;       if (!actv[0] && !actv[1]) continue;
;       const int tb = 16 * (3 - Dl) + 16 + hh - rt;
;       const bf16* ap0 = sW + (aq * 83 + tb - 4 * (2 * wm)) * 8;
;       const bf16* bp0 = sU + bblk[0] * 136 + 8 * hh;
;       const bf16* bp1 = sU + bblk[1] * 136 + 8 * hh;
;       if (actv[0] && actv[1]) {
; #pragma unroll
;         for (int ks = 0; ks < 8; ++ks) {
;           const s8v a0 = *(const s8v*)(ap0 + 16 * ks), a1 = *(const s8v*)(ap0 - 32 + 16 * ks);
;           const s8v b0 = *(const s8v*)(bp0 + 16 * ks), b1 = *(const s8v*)(bp1 + 16 * ks);
;           acc[0][0] = MFMA(a0, b0, acc[0][0]);
;           acc[1][0] = MFMA(a1, b0, acc[1][0]);
;           acc[0][1] = MFMA(a0, b1, acc[0][1]);
;           acc[1][1] = MFMA(a1, b1, acc[1][1]);
;         }
.LBB0_1147:
	s_or_b64 exec, exec, s[2:3]
	v_add_u32_e32 v66, 3, v123
	v_add_u32_e32 v124, s74, v122
	v_cmp_gt_u32_e64 s[2:3], 16, v66
	v_add_u32_e32 v66, 0x1100, v124
	ds_read_b128 v[70:73], v89 offset:35088
	v_cndmask_b32_e64 v66, v228, v66, s[2:3]
	v_add_u32_e32 v125, v90, v66
	ds_read_b128 v[66:69], v89 offset:35024
	ds_read_b128 v[74:77], v125
	v_add_u32_e32 v78, 0x5500, v124
	s_waitcnt lgkmcnt(0)
	v_mfma_f32_32x32x16_bf16 v[50:65], v[70:73], v[74:77], v[50:65]
	s_addk_i32 s74, 0xfbc0
	s_cmpk_eq_i32 s74, 0xe240
	v_mfma_f32_32x32x16_bf16 v[18:33], v[66:69], v[74:77], v[18:33]
	v_cndmask_b32_e64 v74, v228, v78, s[2:3]
	v_add_u32_e32 v134, v90, v74
	ds_read_b128 v[74:77], v134
	ds_read_b128 v[78:81], v89 offset:35120
	ds_read_b128 v[126:129], v125 offset:32
	s_waitcnt lgkmcnt(2)
	v_mfma_f32_32x32x16_bf16 v[34:49], v[70:73], v[74:77], v[34:49]
	v_mfma_f32_32x32x16_bf16 v[2:17], v[66:69], v[74:77], v[2:17]
	ds_read_b128 v[74:77], v89 offset:35056
	s_waitcnt lgkmcnt(1)
	v_mfma_f32_32x32x16_bf16 v[50:65], v[78:81], v[126:129], v[50:65]
	s_waitcnt lgkmcnt(0)
	v_mfma_f32_32x32x16_bf16 v[18:33], v[74:77], v[126:129], v[18:33]
	ds_read_b128 v[126:129], v134 offset:32
	s_waitcnt lgkmcnt(0)
	v_mfma_f32_32x32x16_bf16 v[34:49], v[78:81], v[126:129], v[34:49]
	v_mfma_f32_32x32x16_bf16 v[2:17], v[74:77], v[126:129], v[2:17]
	ds_read_b128 v[130:133], v125 offset:64
	ds_read_b128 v[200:203], v134 offset:64
	ds_read_b128 v[126:129], v89 offset:35152
	s_waitcnt lgkmcnt(2)
	v_mfma_f32_32x32x16_bf16 v[18:33], v[70:73], v[130:133], v[18:33]
	s_waitcnt lgkmcnt(1)
	v_mfma_f32_32x32x16_bf16 v[2:17], v[70:73], v[200:203], v[2:17]
	s_waitcnt lgkmcnt(0)
	v_mfma_f32_32x32x16_bf16 v[50:65], v[126:129], v[130:133], v[50:65]
	v_mfma_f32_32x32x16_bf16 v[34:49], v[126:129], v[200:203], v[34:49]
	ds_read_b128 v[130:133], v125 offset:96
	ds_read_b128 v[200:203], v134 offset:96
	ds_read_b128 v[70:73], v89 offset:35184
	s_waitcnt lgkmcnt(2)
	v_mfma_f32_32x32x16_bf16 v[18:33], v[78:81], v[130:133], v[18:33]
	s_waitcnt lgkmcnt(1)
	v_mfma_f32_32x32x16_bf16 v[2:17], v[78:81], v[200:203], v[2:17]
	s_waitcnt lgkmcnt(0)
	v_mfma_f32_32x32x16_bf16 v[50:65], v[70:73], v[130:133], v[50:65]
	v_mfma_f32_32x32x16_bf16 v[34:49], v[70:73], v[200:203], v[34:49]
	ds_read_b128 v[130:133], v125 offset:128
	ds_read_b128 v[200:203], v134 offset:128
	ds_read_b128 v[78:81], v89 offset:35216
	s_waitcnt lgkmcnt(2)
	v_mfma_f32_32x32x16_bf16 v[18:33], v[126:129], v[130:133], v[18:33]
	s_waitcnt lgkmcnt(1)
	v_mfma_f32_32x32x16_bf16 v[2:17], v[126:129], v[200:203], v[2:17]
	s_waitcnt lgkmcnt(0)
	v_mfma_f32_32x32x16_bf16 v[50:65], v[78:81], v[130:133], v[50:65]
	v_mfma_f32_32x32x16_bf16 v[34:49], v[78:81], v[200:203], v[34:49]
	ds_read_b128 v[130:133], v125 offset:160
	ds_read_b128 v[200:203], v134 offset:160
	ds_read_b128 v[126:129], v89 offset:35248
	s_waitcnt lgkmcnt(2)
	v_mfma_f32_32x32x16_bf16 v[18:33], v[70:73], v[130:133], v[18:33]
	s_waitcnt lgkmcnt(1)
	v_mfma_f32_32x32x16_bf16 v[2:17], v[70:73], v[200:203], v[2:17]
	s_waitcnt lgkmcnt(0)
	v_mfma_f32_32x32x16_bf16 v[50:65], v[126:129], v[130:133], v[50:65]
	v_mfma_f32_32x32x16_bf16 v[34:49], v[126:129], v[200:203], v[34:49]
	ds_read_b128 v[130:133], v125 offset:192
	ds_read_b128 v[200:203], v134 offset:192
	ds_read_b128 v[70:73], v89 offset:35280
	s_waitcnt lgkmcnt(2)
	v_mfma_f32_32x32x16_bf16 v[18:33], v[78:81], v[130:133], v[18:33]
	s_waitcnt lgkmcnt(1)
	v_mfma_f32_32x32x16_bf16 v[2:17], v[78:81], v[200:203], v[2:17]
	s_waitcnt lgkmcnt(0)
	v_mfma_f32_32x32x16_bf16 v[50:65], v[70:73], v[130:133], v[50:65]
	v_mfma_f32_32x32x16_bf16 v[34:49], v[70:73], v[200:203], v[34:49]
	ds_read_b128 v[70:73], v89 offset:35312
	ds_read_b128 v[78:81], v125 offset:224
	v_add_u32_e32 v130, 0x53f0, v124
	s_waitcnt lgkmcnt(0)
	v_mfma_f32_32x32x16_bf16 v[50:65], v[70:73], v[78:81], v[50:65]
	v_mfma_f32_32x32x16_bf16 v[18:33], v[126:129], v[78:81], v[18:33]
	ds_read_b128 v[78:81], v134 offset:224
	s_waitcnt lgkmcnt(0)
	v_mfma_f32_32x32x16_bf16 v[34:49], v[70:73], v[78:81], v[34:49]
	v_add_u32_e32 v70, 2, v123
	v_cmp_gt_u32_e64 s[2:3], 16, v70
	v_add_u32_e32 v70, 0xff0, v124
	s_nop 0
	v_cndmask_b32_e64 v70, v228, v70, s[2:3]
	v_add_u32_e32 v125, v90, v70
	ds_read_b128 v[70:73], v89 offset:34768
	v_mfma_f32_32x32x16_bf16 v[2:17], v[126:129], v[78:81], v[2:17]
	ds_read_b128 v[126:129], v89 offset:34832
	ds_read_b128 v[78:81], v125
	s_waitcnt lgkmcnt(0)
	v_mfma_f32_32x32x16_bf16 v[50:65], v[126:129], v[78:81], v[50:65]
	v_mfma_f32_32x32x16_bf16 v[18:33], v[70:73], v[78:81], v[18:33]
	v_cndmask_b32_e64 v78, v228, v130, s[2:3]
	v_add_u32_e32 v142, v90, v78
	ds_read_b128 v[78:81], v142
	ds_read_b128 v[130:133], v89 offset:34864
	ds_read_b128 v[134:137], v125 offset:32
	s_waitcnt lgkmcnt(2)
	v_mfma_f32_32x32x16_bf16 v[34:49], v[126:129], v[78:81], v[34:49]
	v_mfma_f32_32x32x16_bf16 v[2:17], v[70:73], v[78:81], v[2:17]
	ds_read_b128 v[78:81], v89 offset:34800
	s_waitcnt lgkmcnt(1)
	v_mfma_f32_32x32x16_bf16 v[50:65], v[130:133], v[134:137], v[50:65]
	s_waitcnt lgkmcnt(0)
	v_mfma_f32_32x32x16_bf16 v[18:33], v[78:81], v[134:137], v[18:33]
	ds_read_b128 v[134:137], v142 offset:32
	s_waitcnt lgkmcnt(0)
	v_mfma_f32_32x32x16_bf16 v[34:49], v[130:133], v[134:137], v[34:49]
	v_mfma_f32_32x32x16_bf16 v[2:17], v[78:81], v[134:137], v[2:17]
	ds_read_b128 v[138:141], v125 offset:64
	ds_read_b128 v[200:203], v142 offset:64
	ds_read_b128 v[134:137], v89 offset:34896
	s_waitcnt lgkmcnt(2)
	v_mfma_f32_32x32x16_bf16 v[18:33], v[126:129], v[138:141], v[18:33]
	s_waitcnt lgkmcnt(1)
	v_mfma_f32_32x32x16_bf16 v[2:17], v[126:129], v[200:203], v[2:17]
	s_waitcnt lgkmcnt(0)
; #define MFMA(a, b, c) __builtin_amdgcn_mfma_f32_32x32x16_bf16((a), (b), (c), 0, 0, 0)
; __device__ __forceinline__ void toeplitz_item(const Params& p, int layer, int half, int c, bf16* sm, int dry, unsigned* done_ctr) {
;     ...
;     for (int Dl = 0; Dl < 4; ++Dl) {
;       const int D = D0 + Dl;
;       bool actv[2];
;       int bblk[2];
; #pragma unroll
;       for (int ni = 0; ni < 2; ++ni) {
;         const int nlo = 32 * wn + 64 * ni;
;         actv[ni] = half ? true : !((nlo + 31 - D < 0) || (nlo - D >= 128));
;         const int n = nlo + r;
;         const int src = n - D;
;         const bool valid = half ? ((unsigned)((n & 15) - D) < 16u) : ((unsigned)src < 128u);
;         bblk[ni] = valid ? src : 128;
;       }
;       if (!actv[0] && !actv[1]) continue;
;       const int tb = 16 * (3 - Dl) + 16 + hh - rt;
;       const bf16* ap0 = sW + (aq * 83 + tb - 4 * (2 * wm)) * 8;
;       const bf16* bp0 = sU + bblk[0] * 136 + 8 * hh;
;       const bf16* bp1 = sU + bblk[1] * 136 + 8 * hh;
;       if (actv[0] && actv[1]) {
; #pragma unroll
;         for (int ks = 0; ks < 8; ++ks) {
;           const s8v a0 = *(const s8v*)(ap0 + 16 * ks), a1 = *(const s8v*)(ap0 - 32 + 16 * ks);
;           const s8v b0 = *(const s8v*)(bp0 + 16 * ks), b1 = *(const s8v*)(bp1 + 16 * ks);
;           acc[0][0] = MFMA(a0, b0, acc[0][0]);
;           acc[1][0] = MFMA(a1, b0, acc[1][0]);
;           acc[0][1] = MFMA(a0, b1, acc[0][1]);
;           acc[1][1] = MFMA(a1, b1, acc[1][1]);
;         }
	v_mfma_f32_32x32x16_bf16 v[50:65], v[134:137], v[138:141], v[50:65]
	v_mfma_f32_32x32x16_bf16 v[34:49], v[134:137], v[200:203], v[34:49]
	ds_read_b128 v[138:141], v125 offset:96
	ds_read_b128 v[200:203], v142 offset:96
	ds_read_b128 v[126:129], v89 offset:34928
	s_waitcnt lgkmcnt(2)
	v_mfma_f32_32x32x16_bf16 v[18:33], v[130:133], v[138:141], v[18:33]
	s_waitcnt lgkmcnt(1)
	v_mfma_f32_32x32x16_bf16 v[2:17], v[130:133], v[200:203], v[2:17]
	s_waitcnt lgkmcnt(0)
	v_mfma_f32_32x32x16_bf16 v[50:65], v[126:129], v[138:141], v[50:65]
	v_mfma_f32_32x32x16_bf16 v[34:49], v[126:129], v[200:203], v[34:49]
	ds_read_b128 v[138:141], v125 offset:128
	ds_read_b128 v[200:203], v142 offset:128
	ds_read_b128 v[130:133], v89 offset:34960
	s_waitcnt lgkmcnt(2)
	v_mfma_f32_32x32x16_bf16 v[18:33], v[134:137], v[138:141], v[18:33]
	s_waitcnt lgkmcnt(1)
	v_mfma_f32_32x32x16_bf16 v[2:17], v[134:137], v[200:203], v[2:17]
	s_waitcnt lgkmcnt(0)
	v_mfma_f32_32x32x16_bf16 v[50:65], v[130:133], v[138:141], v[50:65]
	v_mfma_f32_32x32x16_bf16 v[34:49], v[130:133], v[200:203], v[34:49]
	ds_read_b128 v[134:137], v89 offset:34992
	ds_read_b128 v[138:141], v125 offset:160
	s_waitcnt lgkmcnt(0)
	v_mfma_f32_32x32x16_bf16 v[50:65], v[134:137], v[138:141], v[50:65]
	v_mfma_f32_32x32x16_bf16 v[18:33], v[126:129], v[138:141], v[18:33]
	ds_read_b128 v[138:141], v142 offset:160
	s_waitcnt lgkmcnt(0)
	v_mfma_f32_32x32x16_bf16 v[2:17], v[126:129], v[138:141], v[2:17]
	ds_read_b128 v[126:129], v125 offset:192
	v_mfma_f32_32x32x16_bf16 v[34:49], v[134:137], v[138:141], v[34:49]
	s_waitcnt lgkmcnt(0)
	v_mfma_f32_32x32x16_bf16 v[50:65], v[66:69], v[126:129], v[50:65]
	v_mfma_f32_32x32x16_bf16 v[18:33], v[130:133], v[126:129], v[18:33]
	ds_read_b128 v[126:129], v142 offset:192
	s_waitcnt lgkmcnt(0)
	v_mfma_f32_32x32x16_bf16 v[34:49], v[66:69], v[126:129], v[34:49]
	ds_read_b128 v[66:69], v125 offset:224
	v_mfma_f32_32x32x16_bf16 v[2:17], v[130:133], v[126:129], v[2:17]
	ds_read_b128 v[126:129], v89 offset:34576
	v_add_u32_e32 v130, 0x52e0, v124
	s_waitcnt lgkmcnt(1)
	v_mfma_f32_32x32x16_bf16 v[50:65], v[74:77], v[66:69], v[50:65]
	v_mfma_f32_32x32x16_bf16 v[18:33], v[134:137], v[66:69], v[18:33]
	ds_read_b128 v[66:69], v142 offset:224
	s_waitcnt lgkmcnt(0)
	v_mfma_f32_32x32x16_bf16 v[34:49], v[74:77], v[66:69], v[34:49]
	v_mfma_f32_32x32x16_bf16 v[2:17], v[134:137], v[66:69], v[2:17]
	v_add_u32_e32 v66, 1, v123
	v_cmp_gt_u32_e64 s[2:3], 16, v66
	v_add_u32_e32 v66, 0xee0, v124
	s_nop 0
	v_cndmask_b32_e64 v66, v228, v66, s[2:3]
	v_add_u32_e32 v125, v90, v66
	ds_read_b128 v[66:69], v89 offset:34512
	ds_read_b128 v[74:77], v125
	s_waitcnt lgkmcnt(0)
	v_mfma_f32_32x32x16_bf16 v[50:65], v[126:129], v[74:77], v[50:65]
	v_mfma_f32_32x32x16_bf16 v[18:33], v[66:69], v[74:77], v[18:33]
	v_cndmask_b32_e64 v74, v228, v130, s[2:3]
	v_add_u32_e32 v142, v90, v74
	ds_read_b128 v[74:77], v142
	ds_read_b128 v[130:133], v89 offset:34608
	ds_read_b128 v[134:137], v125 offset:32
	v_cmp_gt_u32_e64 s[2:3], 16, v123
	v_add_u32_e32 v123, -4, v123
	s_waitcnt lgkmcnt(2)
	v_mfma_f32_32x32x16_bf16 v[34:49], v[126:129], v[74:77], v[34:49]
	v_mfma_f32_32x32x16_bf16 v[2:17], v[66:69], v[74:77], v[2:17]
	ds_read_b128 v[74:77], v89 offset:34544
	s_waitcnt lgkmcnt(1)
	v_mfma_f32_32x32x16_bf16 v[50:65], v[130:133], v[134:137], v[50:65]
	s_waitcnt lgkmcnt(0)
	v_mfma_f32_32x32x16_bf16 v[18:33], v[74:77], v[134:137], v[18:33]
	ds_read_b128 v[134:137], v142 offset:32
	s_waitcnt lgkmcnt(0)
	v_mfma_f32_32x32x16_bf16 v[34:49], v[130:133], v[134:137], v[34:49]
	v_mfma_f32_32x32x16_bf16 v[2:17], v[74:77], v[134:137], v[2:17]
	ds_read_b128 v[138:141], v125 offset:64
	ds_read_b128 v[200:203], v142 offset:64
	ds_read_b128 v[134:137], v89 offset:34640
	s_waitcnt lgkmcnt(2)
	v_mfma_f32_32x32x16_bf16 v[18:33], v[126:129], v[138:141], v[18:33]
	s_waitcnt lgkmcnt(1)
	v_mfma_f32_32x32x16_bf16 v[2:17], v[126:129], v[200:203], v[2:17]
	s_waitcnt lgkmcnt(0)
	v_mfma_f32_32x32x16_bf16 v[50:65], v[134:137], v[138:141], v[50:65]
	v_mfma_f32_32x32x16_bf16 v[34:49], v[134:137], v[200:203], v[34:49]
	ds_read_b128 v[138:141], v125 offset:96
	ds_read_b128 v[200:203], v142 offset:96
	ds_read_b128 v[126:129], v89 offset:34672
	s_waitcnt lgkmcnt(2)
	v_mfma_f32_32x32x16_bf16 v[18:33], v[130:133], v[138:141], v[18:33]
	s_waitcnt lgkmcnt(1)
	v_mfma_f32_32x32x16_bf16 v[2:17], v[130:133], v[200:203], v[2:17]
	s_waitcnt lgkmcnt(0)
	v_mfma_f32_32x32x16_bf16 v[50:65], v[126:129], v[138:141], v[50:65]
	v_mfma_f32_32x32x16_bf16 v[34:49], v[126:129], v[200:203], v[34:49]
	ds_read_b128 v[138:141], v125 offset:128
	ds_read_b128 v[200:203], v142 offset:128
	ds_read_b128 v[130:133], v89 offset:34704
	s_waitcnt lgkmcnt(2)
	v_mfma_f32_32x32x16_bf16 v[18:33], v[134:137], v[138:141], v[18:33]
	s_waitcnt lgkmcnt(1)
	v_mfma_f32_32x32x16_bf16 v[2:17], v[134:137], v[200:203], v[2:17]
	s_waitcnt lgkmcnt(0)
	v_mfma_f32_32x32x16_bf16 v[50:65], v[130:133], v[138:141], v[50:65]
	v_mfma_f32_32x32x16_bf16 v[34:49], v[130:133], v[200:203], v[34:49]
	ds_read_b128 v[134:137], v89 offset:34736
	ds_read_b128 v[138:141], v125 offset:160
	s_waitcnt lgkmcnt(0)
; #define MFMA(a, b, c) __builtin_amdgcn_mfma_f32_32x32x16_bf16((a), (b), (c), 0, 0, 0)
; __device__ __forceinline__ void toeplitz_item(const Params& p, int layer, int half, int c, bf16* sm, int dry, unsigned* done_ctr) {
;     ...
;     for (int Dl = 0; Dl < 4; ++Dl) {
;       const int D = D0 + Dl;
;       bool actv[2];
;       int bblk[2];
; #pragma unroll
;       for (int ni = 0; ni < 2; ++ni) {
;         const int nlo = 32 * wn + 64 * ni;
;         actv[ni] = half ? true : !((nlo + 31 - D < 0) || (nlo - D >= 128));
;         const int n = nlo + r;
;         const int src = n - D;
;         const bool valid = half ? ((unsigned)((n & 15) - D) < 16u) : ((unsigned)src < 128u);
;         bblk[ni] = valid ? src : 128;
;       }
;       if (!actv[0] && !actv[1]) continue;
;       const int tb = 16 * (3 - Dl) + 16 + hh - rt;
;       const bf16* ap0 = sW + (aq * 83 + tb - 4 * (2 * wm)) * 8;
;       const bf16* bp0 = sU + bblk[0] * 136 + 8 * hh;
;       const bf16* bp1 = sU + bblk[1] * 136 + 8 * hh;
;       if (actv[0] && actv[1]) {
; #pragma unroll
;         for (int ks = 0; ks < 8; ++ks) {
;           const s8v a0 = *(const s8v*)(ap0 + 16 * ks), a1 = *(const s8v*)(ap0 - 32 + 16 * ks);
;           const s8v b0 = *(const s8v*)(bp0 + 16 * ks), b1 = *(const s8v*)(bp1 + 16 * ks);
;           acc[0][0] = MFMA(a0, b0, acc[0][0]);
;           acc[1][0] = MFMA(a1, b0, acc[1][0]);
;           acc[0][1] = MFMA(a0, b1, acc[0][1]);
;           acc[1][1] = MFMA(a1, b1, acc[1][1]);
;         }
	v_mfma_f32_32x32x16_bf16 v[50:65], v[134:137], v[138:141], v[50:65]
	v_mfma_f32_32x32x16_bf16 v[18:33], v[126:129], v[138:141], v[18:33]
	ds_read_b128 v[138:141], v142 offset:160
	s_waitcnt lgkmcnt(0)
	v_mfma_f32_32x32x16_bf16 v[2:17], v[126:129], v[138:141], v[2:17]
	ds_read_b128 v[126:129], v125 offset:192
	v_mfma_f32_32x32x16_bf16 v[34:49], v[134:137], v[138:141], v[34:49]
	s_waitcnt lgkmcnt(0)
	v_mfma_f32_32x32x16_bf16 v[50:65], v[70:73], v[126:129], v[50:65]
	v_mfma_f32_32x32x16_bf16 v[18:33], v[130:133], v[126:129], v[18:33]
	ds_read_b128 v[126:129], v142 offset:192
	s_waitcnt lgkmcnt(0)
	v_mfma_f32_32x32x16_bf16 v[34:49], v[70:73], v[126:129], v[34:49]
	ds_read_b128 v[70:73], v125 offset:224
	v_mfma_f32_32x32x16_bf16 v[2:17], v[130:133], v[126:129], v[2:17]
	ds_read_b128 v[126:129], v89 offset:34256
	s_waitcnt lgkmcnt(1)
	v_mfma_f32_32x32x16_bf16 v[50:65], v[78:81], v[70:73], v[50:65]
	v_mfma_f32_32x32x16_bf16 v[18:33], v[134:137], v[70:73], v[18:33]
	ds_read_b128 v[70:73], v142 offset:224
	s_waitcnt lgkmcnt(0)
	v_mfma_f32_32x32x16_bf16 v[34:49], v[78:81], v[70:73], v[34:49]
	v_add_u32_e32 v78, 0xdd0, v124
	v_cndmask_b32_e64 v78, v228, v78, s[2:3]
	v_add_u32_e32 v132, v90, v78
	ds_read_b128 v[78:81], v132
	v_add_u32_e32 v124, 0x51d0, v124
	v_mfma_f32_32x32x16_bf16 v[2:17], v[134:137], v[70:73], v[2:17]
	ds_read_b128 v[70:73], v89 offset:34320
	s_waitcnt lgkmcnt(0)
	v_mfma_f32_32x32x16_bf16 v[50:65], v[70:73], v[78:81], v[50:65]
	v_mfma_f32_32x32x16_bf16 v[18:33], v[126:129], v[78:81], v[18:33]
	v_cndmask_b32_e64 v78, v228, v124, s[2:3]
	v_add_u32_e32 v133, v90, v78
	ds_read_b128 v[78:81], v133
	s_movk_i32 s2, 0xfc00
	s_mov_b32 s3, -1
	v_lshl_add_u64 v[82:83], v[82:83], 0, s[2:3]
	v_lshl_add_u64 v[84:85], v[84:85], 0, s[2:3]
	s_waitcnt lgkmcnt(0)
	v_mfma_f32_32x32x16_bf16 v[34:49], v[70:73], v[78:81], v[34:49]
	v_lshl_add_u64 v[86:87], v[86:87], 0, s[2:3]
	v_mfma_f32_32x32x16_bf16 v[2:17], v[126:129], v[78:81], v[2:17]
	ds_read_b128 v[78:81], v89 offset:34352
	ds_read_b128 v[124:127], v132 offset:32
	ds_read_b128 v[128:131], v89 offset:34288
	s_waitcnt lgkmcnt(1)
	v_mfma_f32_32x32x16_bf16 v[50:65], v[78:81], v[124:127], v[50:65]
	s_waitcnt lgkmcnt(0)
	v_mfma_f32_32x32x16_bf16 v[18:33], v[128:131], v[124:127], v[18:33]
	ds_read_b128 v[124:127], v133 offset:32
	s_waitcnt lgkmcnt(0)
	v_mfma_f32_32x32x16_bf16 v[34:49], v[78:81], v[124:127], v[34:49]
	v_mfma_f32_32x32x16_bf16 v[2:17], v[128:131], v[124:127], v[2:17]
	ds_read_b128 v[128:131], v132 offset:64
	ds_read_b128 v[200:203], v133 offset:64
	ds_read_b128 v[124:127], v89 offset:34384
	s_waitcnt lgkmcnt(2)
	v_mfma_f32_32x32x16_bf16 v[18:33], v[70:73], v[128:131], v[18:33]
	s_waitcnt lgkmcnt(1)
	v_mfma_f32_32x32x16_bf16 v[2:17], v[70:73], v[200:203], v[2:17]
	s_waitcnt lgkmcnt(0)
	v_mfma_f32_32x32x16_bf16 v[50:65], v[124:127], v[128:131], v[50:65]
	v_mfma_f32_32x32x16_bf16 v[34:49], v[124:127], v[200:203], v[34:49]
	ds_read_b128 v[128:131], v132 offset:96
	ds_read_b128 v[200:203], v133 offset:96
	ds_read_b128 v[70:73], v89 offset:34416
	s_waitcnt lgkmcnt(2)
	v_mfma_f32_32x32x16_bf16 v[18:33], v[78:81], v[128:131], v[18:33]
	s_waitcnt lgkmcnt(1)
	v_mfma_f32_32x32x16_bf16 v[2:17], v[78:81], v[200:203], v[2:17]
	s_waitcnt lgkmcnt(0)
	v_mfma_f32_32x32x16_bf16 v[50:65], v[70:73], v[128:131], v[50:65]
	v_mfma_f32_32x32x16_bf16 v[34:49], v[70:73], v[200:203], v[34:49]
	ds_read_b128 v[128:131], v132 offset:128
	ds_read_b128 v[200:203], v133 offset:128
	ds_read_b128 v[78:81], v89 offset:34448
	s_waitcnt lgkmcnt(2)
	v_mfma_f32_32x32x16_bf16 v[18:33], v[124:127], v[128:131], v[18:33]
	s_waitcnt lgkmcnt(1)
	v_mfma_f32_32x32x16_bf16 v[2:17], v[124:127], v[200:203], v[2:17]
	s_waitcnt lgkmcnt(0)
	v_mfma_f32_32x32x16_bf16 v[50:65], v[78:81], v[128:131], v[50:65]
	v_mfma_f32_32x32x16_bf16 v[34:49], v[78:81], v[200:203], v[34:49]
	ds_read_b128 v[124:127], v89 offset:34480
	ds_read_b128 v[128:131], v132 offset:160
	s_waitcnt lgkmcnt(0)
	v_mfma_f32_32x32x16_bf16 v[50:65], v[124:127], v[128:131], v[50:65]
	v_mfma_f32_32x32x16_bf16 v[18:33], v[70:73], v[128:131], v[18:33]
	ds_read_b128 v[128:131], v133 offset:160
	s_waitcnt lgkmcnt(0)
	v_mfma_f32_32x32x16_bf16 v[2:17], v[70:73], v[128:131], v[2:17]
	ds_read_b128 v[70:73], v132 offset:192
	v_mfma_f32_32x32x16_bf16 v[34:49], v[124:127], v[128:131], v[34:49]
	s_waitcnt lgkmcnt(0)
	v_mfma_f32_32x32x16_bf16 v[50:65], v[66:69], v[70:73], v[50:65]
	v_mfma_f32_32x32x16_bf16 v[18:33], v[78:81], v[70:73], v[18:33]
	ds_read_b128 v[70:73], v133 offset:192
	s_waitcnt lgkmcnt(0)
	v_mfma_f32_32x32x16_bf16 v[34:49], v[66:69], v[70:73], v[34:49]
	ds_read_b128 v[66:69], v132 offset:224
	v_mfma_f32_32x32x16_bf16 v[2:17], v[78:81], v[70:73], v[2:17]
	s_waitcnt lgkmcnt(0)
	v_mfma_f32_32x32x16_bf16 v[50:65], v[74:77], v[66:69], v[50:65]
	v_mfma_f32_32x32x16_bf16 v[18:33], v[124:127], v[66:69], v[18:33]
	ds_read_b128 v[66:69], v133 offset:224
	s_waitcnt lgkmcnt(0)
	v_mfma_f32_32x32x16_bf16 v[34:49], v[74:77], v[66:69], v[34:49]
	v_mfma_f32_32x32x16_bf16 v[2:17], v[124:127], v[66:69], v[2:17]
	s_cbranch_scc1 .LBB0_1205

; #define MFMA(a, b, c) __builtin_amdgcn_mfma_f32_32x32x16_bf16((a), (b), (c), 0, 0, 0)
; __device__ __forceinline__ void toeplitz_item(const Params& p, int layer, int half, int c, bf16* sm, int dry, unsigned* done_ctr) {
;     ...
;       if (actv[0] && actv[1]) {
; #pragma unroll
;         for (int ks = 0; ks < 8; ++ks) {
;           const s8v a0 = *(const s8v*)(ap0 + 16 * ks), a1 = *(const s8v*)(ap0 - 32 + 16 * ks);
;           const s8v b0 = *(const s8v*)(bp0 + 16 * ks), b1 = *(const s8v*)(bp1 + 16 * ks);
;           acc[0][0] = MFMA(a0, b0, acc[0][0]);
;           acc[1][0] = MFMA(a1, b0, acc[1][0]);
;           acc[0][1] = MFMA(a0, b1, acc[0][1]);
;           acc[1][1] = MFMA(a1, b1, acc[1][1]);
;         }
.LBB0_1429:
	s_andn2_saveexec_b64 s[94:95], s[20:21]
	s_cbranch_execz .LBB0_1431
	v_add_u32_e32 v14, v106, v14
	s_waitcnt lgkmcnt(0)
	ds_read_b128 v[6:9], v14
	v_add_u32_e32 v15, v106, v15
	s_waitcnt lgkmcnt(0)
	v_mfma_f32_32x32x16_bf16 v[64:79], v[2:5], v[6:9], v[64:79]
	v_mfma_f32_32x32x16_bf16 v[32:47], v[84:87], v[6:9], v[32:47]
	ds_read_b128 v[6:9], v15
	s_waitcnt lgkmcnt(0)
	v_mfma_f32_32x32x16_bf16 v[48:63], v[2:5], v[6:9], v[48:63]
	v_mfma_f32_32x32x16_bf16 v[16:31], v[84:87], v[6:9], v[16:31]
	ds_read_b128 v[6:9], v108 offset:35120
	ds_read_b128 v[10:13], v14 offset:32
	ds_read_b128 v[80:83], v108 offset:35056
	s_waitcnt lgkmcnt(1)
	v_mfma_f32_32x32x16_bf16 v[64:79], v[6:9], v[10:13], v[64:79]
	s_waitcnt lgkmcnt(0)
	v_mfma_f32_32x32x16_bf16 v[32:47], v[80:83], v[10:13], v[32:47]
	ds_read_b128 v[10:13], v15 offset:32
	s_waitcnt lgkmcnt(0)
	v_mfma_f32_32x32x16_bf16 v[48:63], v[6:9], v[10:13], v[48:63]
	v_mfma_f32_32x32x16_bf16 v[16:31], v[80:83], v[10:13], v[16:31]
	ds_read_b128 v[80:83], v14 offset:64
	ds_read_b128 v[200:203], v15 offset:64
	ds_read_b128 v[10:13], v108 offset:35152
	s_waitcnt lgkmcnt(2)
	v_mfma_f32_32x32x16_bf16 v[32:47], v[2:5], v[80:83], v[32:47]
	s_waitcnt lgkmcnt(1)
	v_mfma_f32_32x32x16_bf16 v[16:31], v[2:5], v[200:203], v[16:31]
	s_waitcnt lgkmcnt(0)
	v_mfma_f32_32x32x16_bf16 v[64:79], v[10:13], v[80:83], v[64:79]
	v_mfma_f32_32x32x16_bf16 v[48:63], v[10:13], v[200:203], v[48:63]
	ds_read_b128 v[80:83], v14 offset:96
	ds_read_b128 v[200:203], v15 offset:96
	ds_read_b128 v[2:5], v108 offset:35184
	s_waitcnt lgkmcnt(2)
	v_mfma_f32_32x32x16_bf16 v[32:47], v[6:9], v[80:83], v[32:47]
	s_waitcnt lgkmcnt(1)
	v_mfma_f32_32x32x16_bf16 v[16:31], v[6:9], v[200:203], v[16:31]
	s_waitcnt lgkmcnt(0)
	v_mfma_f32_32x32x16_bf16 v[64:79], v[2:5], v[80:83], v[64:79]
	v_mfma_f32_32x32x16_bf16 v[48:63], v[2:5], v[200:203], v[48:63]
	ds_read_b128 v[80:83], v14 offset:128
	ds_read_b128 v[200:203], v15 offset:128
	ds_read_b128 v[6:9], v108 offset:35216
	s_waitcnt lgkmcnt(2)
	v_mfma_f32_32x32x16_bf16 v[32:47], v[10:13], v[80:83], v[32:47]
	s_waitcnt lgkmcnt(1)
	v_mfma_f32_32x32x16_bf16 v[16:31], v[10:13], v[200:203], v[16:31]
	s_waitcnt lgkmcnt(0)
	v_mfma_f32_32x32x16_bf16 v[64:79], v[6:9], v[80:83], v[64:79]
	v_mfma_f32_32x32x16_bf16 v[48:63], v[6:9], v[200:203], v[48:63]
	ds_read_b128 v[80:83], v14 offset:160
	ds_read_b128 v[200:203], v15 offset:160
	ds_read_b128 v[10:13], v108 offset:35248
	s_waitcnt lgkmcnt(2)
	v_mfma_f32_32x32x16_bf16 v[32:47], v[2:5], v[80:83], v[32:47]
	s_waitcnt lgkmcnt(1)
	v_mfma_f32_32x32x16_bf16 v[16:31], v[2:5], v[200:203], v[16:31]
	s_waitcnt lgkmcnt(0)
	v_mfma_f32_32x32x16_bf16 v[64:79], v[10:13], v[80:83], v[64:79]
	v_mfma_f32_32x32x16_bf16 v[48:63], v[10:13], v[200:203], v[48:63]
	ds_read_b128 v[2:5], v108 offset:35280
	ds_read_b128 v[80:83], v14 offset:192
	s_waitcnt lgkmcnt(0)
	v_mfma_f32_32x32x16_bf16 v[64:79], v[2:5], v[80:83], v[64:79]
	v_mfma_f32_32x32x16_bf16 v[32:47], v[6:9], v[80:83], v[32:47]
	ds_read_b128 v[80:83], v15 offset:192
	s_waitcnt lgkmcnt(0)
	v_mfma_f32_32x32x16_bf16 v[48:63], v[2:5], v[80:83], v[48:63]
	v_mfma_f32_32x32x16_bf16 v[16:31], v[6:9], v[80:83], v[16:31]
	ds_read_b128 v[2:5], v108 offset:35312
	ds_read_b128 v[6:9], v14 offset:224
	s_waitcnt lgkmcnt(0)
	v_mfma_f32_32x32x16_bf16 v[64:79], v[2:5], v[6:9], v[64:79]
	v_mfma_f32_32x32x16_bf16 v[32:47], v[10:13], v[6:9], v[32:47]
	ds_read_b128 v[6:9], v15 offset:224
	s_waitcnt lgkmcnt(0)
	v_mfma_f32_32x32x16_bf16 v[48:63], v[2:5], v[6:9], v[48:63]
	v_mfma_f32_32x32x16_bf16 v[16:31], v[10:13], v[6:9], v[16:31]

; #define MFMA(a, b, c) __builtin_amdgcn_mfma_f32_32x32x16_bf16((a), (b), (c), 0, 0, 0)
; __device__ __forceinline__ void toeplitz_item(const Params& p, int layer, int half, int c, bf16* sm, int dry, unsigned* done_ctr) {
;     ...
;       if (actv[0] && actv[1]) {
; #pragma unroll
;         for (int ks = 0; ks < 8; ++ks) {
;           const s8v a0 = *(const s8v*)(ap0 + 16 * ks), a1 = *(const s8v*)(ap0 - 32 + 16 * ks);
;           const s8v b0 = *(const s8v*)(bp0 + 16 * ks), b1 = *(const s8v*)(bp1 + 16 * ks);
;           acc[0][0] = MFMA(a0, b0, acc[0][0]);
;           acc[1][0] = MFMA(a1, b0, acc[1][0]);
;           acc[0][1] = MFMA(a0, b1, acc[0][1]);
;           acc[1][1] = MFMA(a1, b1, acc[1][1]);
;         }
.LBB0_1439:
	s_andn2_saveexec_b64 s[20:21], s[20:21]
	s_cbranch_execz .LBB0_1441
	v_add_u32_e32 v14, v106, v14
	s_waitcnt lgkmcnt(0)
	ds_read_b128 v[6:9], v14
	v_add_u32_e32 v15, v106, v15
	s_waitcnt lgkmcnt(0)
	v_mfma_f32_32x32x16_bf16 v[64:79], v[2:5], v[6:9], v[64:79]
	v_mfma_f32_32x32x16_bf16 v[32:47], v[84:87], v[6:9], v[32:47]
	ds_read_b128 v[6:9], v15
	s_waitcnt lgkmcnt(0)
	v_mfma_f32_32x32x16_bf16 v[48:63], v[2:5], v[6:9], v[48:63]
	v_mfma_f32_32x32x16_bf16 v[16:31], v[84:87], v[6:9], v[16:31]
	ds_read_b128 v[6:9], v108 offset:34864
	ds_read_b128 v[10:13], v14 offset:32
	ds_read_b128 v[80:83], v108 offset:34800
	s_waitcnt lgkmcnt(1)
	v_mfma_f32_32x32x16_bf16 v[64:79], v[6:9], v[10:13], v[64:79]
	s_waitcnt lgkmcnt(0)
	v_mfma_f32_32x32x16_bf16 v[32:47], v[80:83], v[10:13], v[32:47]
	ds_read_b128 v[10:13], v15 offset:32
	s_waitcnt lgkmcnt(0)
	v_mfma_f32_32x32x16_bf16 v[48:63], v[6:9], v[10:13], v[48:63]
	v_mfma_f32_32x32x16_bf16 v[16:31], v[80:83], v[10:13], v[16:31]
	ds_read_b128 v[80:83], v14 offset:64
	ds_read_b128 v[200:203], v15 offset:64
	ds_read_b128 v[10:13], v108 offset:34896
	s_waitcnt lgkmcnt(2)
	v_mfma_f32_32x32x16_bf16 v[32:47], v[2:5], v[80:83], v[32:47]
	s_waitcnt lgkmcnt(1)
	v_mfma_f32_32x32x16_bf16 v[16:31], v[2:5], v[200:203], v[16:31]
	s_waitcnt lgkmcnt(0)
	v_mfma_f32_32x32x16_bf16 v[64:79], v[10:13], v[80:83], v[64:79]
	v_mfma_f32_32x32x16_bf16 v[48:63], v[10:13], v[200:203], v[48:63]
	ds_read_b128 v[80:83], v14 offset:96
	ds_read_b128 v[200:203], v15 offset:96
	ds_read_b128 v[2:5], v108 offset:34928
	s_waitcnt lgkmcnt(2)
	v_mfma_f32_32x32x16_bf16 v[32:47], v[6:9], v[80:83], v[32:47]
	s_waitcnt lgkmcnt(1)
	v_mfma_f32_32x32x16_bf16 v[16:31], v[6:9], v[200:203], v[16:31]
	s_waitcnt lgkmcnt(0)
	v_mfma_f32_32x32x16_bf16 v[64:79], v[2:5], v[80:83], v[64:79]
	v_mfma_f32_32x32x16_bf16 v[48:63], v[2:5], v[200:203], v[48:63]
	ds_read_b128 v[80:83], v14 offset:128
	ds_read_b128 v[200:203], v15 offset:128
	ds_read_b128 v[6:9], v108 offset:34960
	s_waitcnt lgkmcnt(2)
	v_mfma_f32_32x32x16_bf16 v[32:47], v[10:13], v[80:83], v[32:47]
	s_waitcnt lgkmcnt(1)
	v_mfma_f32_32x32x16_bf16 v[16:31], v[10:13], v[200:203], v[16:31]
	s_waitcnt lgkmcnt(0)
	v_mfma_f32_32x32x16_bf16 v[64:79], v[6:9], v[80:83], v[64:79]
	v_mfma_f32_32x32x16_bf16 v[48:63], v[6:9], v[200:203], v[48:63]
	ds_read_b128 v[80:83], v14 offset:160
	ds_read_b128 v[200:203], v15 offset:160
	ds_read_b128 v[10:13], v108 offset:34992
	s_waitcnt lgkmcnt(2)
	v_mfma_f32_32x32x16_bf16 v[32:47], v[2:5], v[80:83], v[32:47]
	s_waitcnt lgkmcnt(1)
	v_mfma_f32_32x32x16_bf16 v[16:31], v[2:5], v[200:203], v[16:31]
	s_waitcnt lgkmcnt(0)
	v_mfma_f32_32x32x16_bf16 v[64:79], v[10:13], v[80:83], v[64:79]
	v_mfma_f32_32x32x16_bf16 v[48:63], v[10:13], v[200:203], v[48:63]
	ds_read_b128 v[2:5], v108 offset:35024
	ds_read_b128 v[80:83], v14 offset:192
	s_waitcnt lgkmcnt(0)
	v_mfma_f32_32x32x16_bf16 v[64:79], v[2:5], v[80:83], v[64:79]
	v_mfma_f32_32x32x16_bf16 v[32:47], v[6:9], v[80:83], v[32:47]
	ds_read_b128 v[80:83], v15 offset:192
	s_waitcnt lgkmcnt(0)
	v_mfma_f32_32x32x16_bf16 v[48:63], v[2:5], v[80:83], v[48:63]
	v_mfma_f32_32x32x16_bf16 v[16:31], v[6:9], v[80:83], v[16:31]
	ds_read_b128 v[2:5], v108 offset:35056
	ds_read_b128 v[6:9], v14 offset:224
	s_waitcnt lgkmcnt(0)
	v_mfma_f32_32x32x16_bf16 v[64:79], v[2:5], v[6:9], v[64:79]
	v_mfma_f32_32x32x16_bf16 v[32:47], v[10:13], v[6:9], v[32:47]
	ds_read_b128 v[6:9], v15 offset:224
	s_waitcnt lgkmcnt(0)
	v_mfma_f32_32x32x16_bf16 v[48:63], v[2:5], v[6:9], v[48:63]
	v_mfma_f32_32x32x16_bf16 v[16:31], v[10:13], v[6:9], v[16:31]

; #define MFMA(a, b, c) __builtin_amdgcn_mfma_f32_32x32x16_bf16((a), (b), (c), 0, 0, 0)
; __device__ __forceinline__ void toeplitz_item(const Params& p, int layer, int half, int c, bf16* sm, int dry, unsigned* done_ctr) {
;     ...
;       if (actv[0] && actv[1]) {
; #pragma unroll
;         for (int ks = 0; ks < 8; ++ks) {
;           const s8v a0 = *(const s8v*)(ap0 + 16 * ks), a1 = *(const s8v*)(ap0 - 32 + 16 * ks);
;           const s8v b0 = *(const s8v*)(bp0 + 16 * ks), b1 = *(const s8v*)(bp1 + 16 * ks);
;           acc[0][0] = MFMA(a0, b0, acc[0][0]);
;           acc[1][0] = MFMA(a1, b0, acc[1][0]);
;           acc[0][1] = MFMA(a0, b1, acc[0][1]);
;           acc[1][1] = MFMA(a1, b1, acc[1][1]);
;         }
.LBB0_1449:
	s_andn2_saveexec_b64 s[20:21], s[20:21]
	s_cbranch_execz .LBB0_1451
	v_add_u32_e32 v14, v106, v14
	s_waitcnt lgkmcnt(0)
	ds_read_b128 v[6:9], v14
	v_add_u32_e32 v15, v106, v15
	s_waitcnt lgkmcnt(0)
	v_mfma_f32_32x32x16_bf16 v[64:79], v[2:5], v[6:9], v[64:79]
	v_mfma_f32_32x32x16_bf16 v[32:47], v[84:87], v[6:9], v[32:47]
	ds_read_b128 v[6:9], v15
	s_waitcnt lgkmcnt(0)
	v_mfma_f32_32x32x16_bf16 v[48:63], v[2:5], v[6:9], v[48:63]
	v_mfma_f32_32x32x16_bf16 v[16:31], v[84:87], v[6:9], v[16:31]
	ds_read_b128 v[6:9], v108 offset:34608
	ds_read_b128 v[10:13], v14 offset:32
	ds_read_b128 v[80:83], v108 offset:34544
	s_waitcnt lgkmcnt(1)
	v_mfma_f32_32x32x16_bf16 v[64:79], v[6:9], v[10:13], v[64:79]
	s_waitcnt lgkmcnt(0)
	v_mfma_f32_32x32x16_bf16 v[32:47], v[80:83], v[10:13], v[32:47]
	ds_read_b128 v[10:13], v15 offset:32
	s_waitcnt lgkmcnt(0)
	v_mfma_f32_32x32x16_bf16 v[48:63], v[6:9], v[10:13], v[48:63]
	v_mfma_f32_32x32x16_bf16 v[16:31], v[80:83], v[10:13], v[16:31]
	ds_read_b128 v[80:83], v14 offset:64
	ds_read_b128 v[200:203], v15 offset:64
	ds_read_b128 v[10:13], v108 offset:34640
	s_waitcnt lgkmcnt(2)
	v_mfma_f32_32x32x16_bf16 v[32:47], v[2:5], v[80:83], v[32:47]
	s_waitcnt lgkmcnt(1)
	v_mfma_f32_32x32x16_bf16 v[16:31], v[2:5], v[200:203], v[16:31]
	s_waitcnt lgkmcnt(0)
	v_mfma_f32_32x32x16_bf16 v[64:79], v[10:13], v[80:83], v[64:79]
	v_mfma_f32_32x32x16_bf16 v[48:63], v[10:13], v[200:203], v[48:63]
	ds_read_b128 v[80:83], v14 offset:96
	ds_read_b128 v[200:203], v15 offset:96
	ds_read_b128 v[2:5], v108 offset:34672
	s_waitcnt lgkmcnt(2)
	v_mfma_f32_32x32x16_bf16 v[32:47], v[6:9], v[80:83], v[32:47]
	s_waitcnt lgkmcnt(1)
	v_mfma_f32_32x32x16_bf16 v[16:31], v[6:9], v[200:203], v[16:31]
	s_waitcnt lgkmcnt(0)
	v_mfma_f32_32x32x16_bf16 v[64:79], v[2:5], v[80:83], v[64:79]
	v_mfma_f32_32x32x16_bf16 v[48:63], v[2:5], v[200:203], v[48:63]
	ds_read_b128 v[80:83], v14 offset:128
	ds_read_b128 v[200:203], v15 offset:128
	ds_read_b128 v[6:9], v108 offset:34704
	s_waitcnt lgkmcnt(2)
	v_mfma_f32_32x32x16_bf16 v[32:47], v[10:13], v[80:83], v[32:47]
	s_waitcnt lgkmcnt(1)
	v_mfma_f32_32x32x16_bf16 v[16:31], v[10:13], v[200:203], v[16:31]
	s_waitcnt lgkmcnt(0)
	v_mfma_f32_32x32x16_bf16 v[64:79], v[6:9], v[80:83], v[64:79]
	v_mfma_f32_32x32x16_bf16 v[48:63], v[6:9], v[200:203], v[48:63]
	ds_read_b128 v[80:83], v14 offset:160
	ds_read_b128 v[200:203], v15 offset:160
	ds_read_b128 v[10:13], v108 offset:34736
	s_waitcnt lgkmcnt(2)
	v_mfma_f32_32x32x16_bf16 v[32:47], v[2:5], v[80:83], v[32:47]
	s_waitcnt lgkmcnt(1)
	v_mfma_f32_32x32x16_bf16 v[16:31], v[2:5], v[200:203], v[16:31]
	s_waitcnt lgkmcnt(0)
	v_mfma_f32_32x32x16_bf16 v[64:79], v[10:13], v[80:83], v[64:79]
	v_mfma_f32_32x32x16_bf16 v[48:63], v[10:13], v[200:203], v[48:63]
	ds_read_b128 v[2:5], v108 offset:34768
	ds_read_b128 v[80:83], v14 offset:192
	s_waitcnt lgkmcnt(0)
	v_mfma_f32_32x32x16_bf16 v[64:79], v[2:5], v[80:83], v[64:79]
	v_mfma_f32_32x32x16_bf16 v[32:47], v[6:9], v[80:83], v[32:47]
	ds_read_b128 v[80:83], v15 offset:192
	s_waitcnt lgkmcnt(0)
	v_mfma_f32_32x32x16_bf16 v[48:63], v[2:5], v[80:83], v[48:63]
	v_mfma_f32_32x32x16_bf16 v[16:31], v[6:9], v[80:83], v[16:31]
	ds_read_b128 v[2:5], v108 offset:34800
	ds_read_b128 v[6:9], v14 offset:224
	s_waitcnt lgkmcnt(0)
	v_mfma_f32_32x32x16_bf16 v[64:79], v[2:5], v[6:9], v[64:79]
	v_mfma_f32_32x32x16_bf16 v[32:47], v[10:13], v[6:9], v[32:47]
	ds_read_b128 v[6:9], v15 offset:224
	s_waitcnt lgkmcnt(0)
	v_mfma_f32_32x32x16_bf16 v[48:63], v[2:5], v[6:9], v[48:63]
	v_mfma_f32_32x32x16_bf16 v[16:31], v[10:13], v[6:9], v[16:31]

; #define MFMA(a, b, c) __builtin_amdgcn_mfma_f32_32x32x16_bf16((a), (b), (c), 0, 0, 0)
; __device__ __forceinline__ void toeplitz_item(const Params& p, int layer, int half, int c, bf16* sm, int dry, unsigned* done_ctr) {
;     ...
;       if (actv[0] && actv[1]) {
; #pragma unroll
;         for (int ks = 0; ks < 8; ++ks) {
;           const s8v a0 = *(const s8v*)(ap0 + 16 * ks), a1 = *(const s8v*)(ap0 - 32 + 16 * ks);
;           const s8v b0 = *(const s8v*)(bp0 + 16 * ks), b1 = *(const s8v*)(bp1 + 16 * ks);
;           acc[0][0] = MFMA(a0, b0, acc[0][0]);
;           acc[1][0] = MFMA(a1, b0, acc[1][0]);
;           acc[0][1] = MFMA(a0, b1, acc[0][1]);
;           acc[1][1] = MFMA(a1, b1, acc[1][1]);
;         }
.LBB0_1459:
	s_andn2_saveexec_b64 s[20:21], s[20:21]
	s_cbranch_execz .LBB0_1369
	v_add_u32_e32 v0, v106, v0
	s_waitcnt lgkmcnt(0)
	ds_read_b128 v[6:9], v0
	v_add_u32_e32 v14, v106, v14
	s_waitcnt lgkmcnt(0)
	v_mfma_f32_32x32x16_bf16 v[64:79], v[2:5], v[6:9], v[64:79]
	v_mfma_f32_32x32x16_bf16 v[32:47], v[84:87], v[6:9], v[32:47]
	ds_read_b128 v[6:9], v14
	s_waitcnt lgkmcnt(0)
	v_mfma_f32_32x32x16_bf16 v[48:63], v[2:5], v[6:9], v[48:63]
	v_mfma_f32_32x32x16_bf16 v[16:31], v[84:87], v[6:9], v[16:31]
	ds_read_b128 v[6:9], v108 offset:34352
	ds_read_b128 v[10:13], v0 offset:32
	ds_read_b128 v[80:83], v108 offset:34288
	s_waitcnt lgkmcnt(1)
	v_mfma_f32_32x32x16_bf16 v[64:79], v[6:9], v[10:13], v[64:79]
	s_waitcnt lgkmcnt(0)
	v_mfma_f32_32x32x16_bf16 v[32:47], v[80:83], v[10:13], v[32:47]
	ds_read_b128 v[10:13], v14 offset:32
	s_waitcnt lgkmcnt(0)
	v_mfma_f32_32x32x16_bf16 v[48:63], v[6:9], v[10:13], v[48:63]
	v_mfma_f32_32x32x16_bf16 v[16:31], v[80:83], v[10:13], v[16:31]
	ds_read_b128 v[80:83], v0 offset:64
	ds_read_b128 v[200:203], v14 offset:64
	ds_read_b128 v[10:13], v108 offset:34384
	s_waitcnt lgkmcnt(2)
	v_mfma_f32_32x32x16_bf16 v[32:47], v[2:5], v[80:83], v[32:47]
	s_waitcnt lgkmcnt(1)
	v_mfma_f32_32x32x16_bf16 v[16:31], v[2:5], v[200:203], v[16:31]
	s_waitcnt lgkmcnt(0)
	v_mfma_f32_32x32x16_bf16 v[64:79], v[10:13], v[80:83], v[64:79]
	v_mfma_f32_32x32x16_bf16 v[48:63], v[10:13], v[200:203], v[48:63]
	ds_read_b128 v[80:83], v0 offset:96
	ds_read_b128 v[200:203], v14 offset:96
	ds_read_b128 v[2:5], v108 offset:34416
	s_waitcnt lgkmcnt(2)
	v_mfma_f32_32x32x16_bf16 v[32:47], v[6:9], v[80:83], v[32:47]
	s_waitcnt lgkmcnt(1)
	v_mfma_f32_32x32x16_bf16 v[16:31], v[6:9], v[200:203], v[16:31]
	s_waitcnt lgkmcnt(0)
	v_mfma_f32_32x32x16_bf16 v[64:79], v[2:5], v[80:83], v[64:79]
	v_mfma_f32_32x32x16_bf16 v[48:63], v[2:5], v[200:203], v[48:63]
	ds_read_b128 v[80:83], v0 offset:128
	ds_read_b128 v[200:203], v14 offset:128
	ds_read_b128 v[6:9], v108 offset:34448
	s_waitcnt lgkmcnt(2)
	v_mfma_f32_32x32x16_bf16 v[32:47], v[10:13], v[80:83], v[32:47]
	s_waitcnt lgkmcnt(1)
	v_mfma_f32_32x32x16_bf16 v[16:31], v[10:13], v[200:203], v[16:31]
	s_waitcnt lgkmcnt(0)
	v_mfma_f32_32x32x16_bf16 v[64:79], v[6:9], v[80:83], v[64:79]
	v_mfma_f32_32x32x16_bf16 v[48:63], v[6:9], v[200:203], v[48:63]
	ds_read_b128 v[80:83], v0 offset:160
	ds_read_b128 v[200:203], v14 offset:160
	ds_read_b128 v[10:13], v108 offset:34480
	s_waitcnt lgkmcnt(2)
	v_mfma_f32_32x32x16_bf16 v[32:47], v[2:5], v[80:83], v[32:47]
	s_waitcnt lgkmcnt(1)
	v_mfma_f32_32x32x16_bf16 v[16:31], v[2:5], v[200:203], v[16:31]
	s_waitcnt lgkmcnt(0)
	v_mfma_f32_32x32x16_bf16 v[64:79], v[10:13], v[80:83], v[64:79]
	v_mfma_f32_32x32x16_bf16 v[48:63], v[10:13], v[200:203], v[48:63]
	ds_read_b128 v[2:5], v108 offset:34512
	ds_read_b128 v[80:83], v0 offset:192
	s_waitcnt lgkmcnt(0)
	v_mfma_f32_32x32x16_bf16 v[64:79], v[2:5], v[80:83], v[64:79]
	v_mfma_f32_32x32x16_bf16 v[32:47], v[6:9], v[80:83], v[32:47]
	ds_read_b128 v[80:83], v14 offset:192
	s_waitcnt lgkmcnt(0)
	v_mfma_f32_32x32x16_bf16 v[48:63], v[2:5], v[80:83], v[48:63]
	v_mfma_f32_32x32x16_bf16 v[16:31], v[6:9], v[80:83], v[16:31]
	ds_read_b128 v[2:5], v108 offset:34544
	ds_read_b128 v[6:9], v0 offset:224
	s_waitcnt lgkmcnt(0)
	v_mfma_f32_32x32x16_bf16 v[64:79], v[2:5], v[6:9], v[64:79]
	v_mfma_f32_32x32x16_bf16 v[32:47], v[10:13], v[6:9], v[32:47]
	ds_read_b128 v[6:9], v14 offset:224
	s_waitcnt lgkmcnt(0)
	v_mfma_f32_32x32x16_bf16 v[48:63], v[2:5], v[6:9], v[48:63]
	v_mfma_f32_32x32x16_bf16 v[16:31], v[10:13], v[6:9], v[16:31]
	s_branch .LBB0_1369
